# mLSTM output items popped chunk-major (the longest chunk of every head first) + mixer priorities (mLSTM output 3, long FoX 2)
# baseline (speedup 1.0000x reference)
; __global__ void __launch_bounds__(512, 2) mega_fwd(Args a) {
;     ...
;                     if (isc && !((okmask >> (8 + xcd)) & 1u)) { unsigned sp = 0u;
;                         while (__hip_atomic_load(done + 8, __ATOMIC_RELAXED, __HIP_MEMORY_SCOPE_AGENT) < 90u) { __builtin_amdgcn_s_sleep(120); if (++sp > (1u << 17)) break; }
;                         __builtin_amdgcn_fence(__ATOMIC_ACQUIRE, "agent"); okmask |= 1u << (8 + xcd); }
;                     if (isc) { const int ci = it - 522; __builtin_amdgcn_s_setprio(2); mlstm_item<true>(ub, yb, mscr, prm + 512, prm + 8, prm + 16, prm + 64, L + wave * ML_WSTRIDE, xcd + 8 * (ci >> 4), 15 - (ci & 15), lane); __builtin_amdgcn_s_setprio(0); }
.LBB0_780:
	s_setprio 3
	s_mul_i32 s0, s3, 43
	s_lshr_b32 s0, s0, 8
	s_mul_i32 s1, s0, 6
	s_sub_i32 s1, s3, s1
	s_lshl_b32 s1, s1, 4
	s_or_b32 s3, s1, s0
	s_lshr_b32 s0, s3, 1
	s_and_b32 s0, s0, 0xfff8
	s_or_b32 s0, s0, s69
	s_and_b32 s1, s0, 0xff
	s_mulk_i32 s1, 0xab
	s_lshr_b32 s50, s1, 10
	s_mul_i32 s1, s50, 6
	s_sub_i32 s0, s0, s1
	s_and_b32 s33, s0, 0xff
	s_lshl_b32 s52, s33, 6
	s_add_i32 s51, s52, 0x140
	s_mov_b64 s[0:1], 0
	v_mov_b32_e32 v1, v220
	v_mov_b32_e32 v4, v202
